# attention unit prologue: second-item conv weights loaded once per unit into VGPRs unused by the attention phase (two in-block reloads with full waits removed); kernarg holder moved v237->v238
# baseline (speedup 1.0000x reference)
_Z9block_fwd4Args:
	v_writelane_b32 v238, s0, 0
	v_writelane_b32 v238, s1, 1
	s_load_dwordx8 s[24:31], s[0:1], 0x80
	s_add_u32 s4, s0, 0x98
	s_addc_u32 s5, s1, 0
	v_and_b32_e32 v208, 0x3ff, v0
	s_mov_b32 s89, s2
	s_waitcnt lgkmcnt(0)
	s_and_b32 s3, s30, 7
	s_cmp_eq_u32 s3, 0
	v_readfirstlane_b32 s56, v208
	s_mov_b32 s33, 0
	s_cselect_b64 s[90:91], -1, 0
	s_cmp_lg_u32 s3, 0
	s_mov_b32 s3, s2
	s_cbranch_scc1 .LBB0_2
	s_ashr_i32 s6, s2, 31
	s_lshr_b32 s6, s6, 29
	s_add_i32 s6, s2, s6
	s_and_b32 s7, s6, -8
	s_ashr_i32 s3, s30, 3
	s_sub_i32 s7, s2, s7
	s_mul_i32 s3, s3, s7
	s_ashr_i32 s6, s6, 3
	s_add_i32 s3, s3, s6

.LBB0_253:
	s_cmp_gt_i32 s29, 1
	s_cselect_b64 s[0:1], -1, 0
	s_and_b64 s[4:5], s[60:61], s[0:1]
	s_andn2_b64 vcc, exec, s[4:5]
	s_cbranch_vccnz .LBB0_303
	s_waitcnt vmcnt(0)
	v_cmp_eq_u32_e32 vcc, 0, v208
	s_waitcnt lgkmcnt(0)
	s_barrier
	v_readfirstlane_b32 s3, v208
	s_nop 3
	s_lshr_b32 s3, s3, 6
	s_cmp_eq_u32 s3, 0
	s_cbranch_scc1 .Lmy_cv0_end
	v_readlane_b32 s36, v238, 0
	v_readlane_b32 s37, v238, 1
	s_mul_i32 s4, s2, 7
	s_add_i32 s4, s4, s3
	s_add_i32 s4, s4, -1
	s_lshl_b32 s72, s3, 14
	s_mov_b32 s3, s4
	s_nop 4
	s_load_dwordx4 s[60:63], s[36:37], 0x60
	s_load_dwordx2 s[64:65], s[36:37], 0x70
	s_load_dwordx2 s[98:99], s[36:37], 0x58
	s_load_dwordx2 s[100:101], s[36:37], 0x48
	v_and_b32_e32 v8, 7, v209
	v_lshrrev_b32_e32 v9, 3, v209
	v_mul_u32_u24_e32 v0, 0x5800, v9
	v_lshl_add_u32 v0, v8, 4, v0
	v_lshlrev_b32_e32 v152, 13, v9
	v_lshl_add_u32 v152, v8, 4, v152
	v_mul_u32_u24_e32 v2, 0x420, v8
	v_lshl_add_u32 v2, v9, 2, v2
	v_add_u32_e32 v2, s72, v2
	v_mul_u32_u24_e32 v3, 0x108, v9
	v_lshl_add_u32 v3, v8, 5, v3
	v_add_u32_e32 v3, s72, v3
	v_lshlrev_b32_e32 v4, 12, v9
	v_lshl_add_u32 v4, v8, 4, v4
	v_lshlrev_b32_e32 v5, 5, v8
	s_waitcnt lgkmcnt(0)
	s_add_i32 s66, s3, 256
	s_lshr_b32 vcc_lo, s66, 6
	s_and_b32 vcc_hi, s66, 63
	s_lshl_b32 s70, vcc_lo, 19
	s_lshl_b32 s71, vcc_hi, 7
	s_add_u32 s68, s98, s70
	s_addc_u32 s69, s99, 0
	s_add_u32 s68, s68, s71
	s_addc_u32 s69, s69, 0
	v_mov_b32_e32 v1, v152
	global_load_dwordx4 v[112:115], v1, s[68:69] nt
	v_add_u32_e32 v1, 0x10000, v1
	global_load_dwordx4 v[116:119], v1, s[68:69] nt
	v_add_u32_e32 v1, 0x10000, v1
	global_load_dwordx4 v[120:123], v1, s[68:69] nt
	v_add_u32_e32 v1, 0x10000, v1
	global_load_dwordx4 v[124:127], v1, s[68:69] nt
	v_add_u32_e32 v1, 0x10000, v1
	global_load_dwordx4 v[128:131], v1, s[68:69] nt
	v_add_u32_e32 v1, 0x10000, v1
	global_load_dwordx4 v[132:135], v1, s[68:69] nt
	v_add_u32_e32 v1, 0x10000, v1
	global_load_dwordx4 v[136:139], v1, s[68:69] nt
	v_add_u32_e32 v1, 0x10000, v1
	global_load_dwordx4 v[140:143], v1, s[68:69] nt
	s_and_b32 s70, vcc_lo, 1
	s_lshl_b32 s70, s70, 8
	s_add_u32 s70, s100, s70
	s_addc_u32 s71, s101, 0
	global_load_dwordx4 v[144:147], v5, s[70:71]
	global_load_dwordx4 v[148:151], v5, s[70:71] offset:16
	s_add_i32 s66, s3, 512
	s_cmpk_ge_u32 s66, 0x1600
	s_cselect_b32 s68, s64, s62
	s_cselect_b32 s69, s65, s63
	s_cselect_b32 s54, 128, 0
	s_cselect_b32 s41, 0x1600, 0
	s_sub_u32 s41, s66, s41
	s_mul_hi_u32 s4, s41, 0xba2e8ba3
	s_lshr_b32 s4, s4, 7
	s_mul_i32 s70, s4, 0xb0
	s_sub_u32 s5, s41, s70
	s_mul_i32 s70, s4, 0x160000
	s_lshl_b32 s71, s5, 7
	s_add_u32 s68, s68, s70
	s_addc_u32 s69, s69, 0
	s_add_u32 s68, s68, s71
	s_addc_u32 s69, s69, 0
	v_mov_b32_e32 v1, v0
	global_load_dwordx4 v[32:35], v1, s[68:69] nt
	v_add_u32_e32 v1, 0x2c000, v1
	global_load_dwordx4 v[36:39], v1, s[68:69] nt
	v_add_u32_e32 v1, 0x2c000, v1
	global_load_dwordx4 v[40:43], v1, s[68:69] nt
	v_add_u32_e32 v1, 0x2c000, v1
	global_load_dwordx4 v[44:47], v1, s[68:69] nt
	v_add_u32_e32 v1, 0x2c000, v1
	global_load_dwordx4 v[48:51], v1, s[68:69] nt
	v_add_u32_e32 v1, 0x2c000, v1
	global_load_dwordx4 v[52:55], v1, s[68:69] nt
	v_add_u32_e32 v1, 0x2c000, v1
	global_load_dwordx4 v[56:59], v1, s[68:69] nt
	v_add_u32_e32 v1, 0x2c000, v1
	global_load_dwordx4 v[60:63], v1, s[68:69] nt
	s_lshl_b32 s70, s4, 8
	s_add_u32 s70, s60, s70
	s_addc_u32 s71, s61, 0
	global_load_dwordx4 v[96:99], v5, s[70:71]
	global_load_dwordx4 v[100:103], v5, s[70:71] offset:16
	s_addk_i32 s66, 0x700
	s_cmpk_ge_u32 s66, 0x1600
	s_cselect_b32 s68, s64, s62
	s_cselect_b32 s69, s65, s63
	s_cselect_b32 s40, 128, 0
	s_cselect_b32 s41, 0x1600, 0
	s_sub_u32 s41, s66, s41
	s_mul_hi_u32 s55, s41, 0xba2e8ba3
	s_lshr_b32 s55, s55, 7
	s_mul_i32 s70, s55, 0xb0
	s_sub_u32 s67, s41, s70
	s_mul_i32 s70, s55, 0x160000
	s_lshl_b32 s71, s67, 7
	s_add_u32 s68, s68, s70
	s_addc_u32 s69, s69, 0
	s_add_u32 s68, s68, s71
	s_addc_u32 s69, s69, 0
	v_mov_b32_e32 v1, v0
	global_load_dwordx4 v[64:67], v1, s[68:69] nt
	v_add_u32_e32 v1, 0x2c000, v1
	global_load_dwordx4 v[68:71], v1, s[68:69] nt
	v_add_u32_e32 v1, 0x2c000, v1
	global_load_dwordx4 v[72:75], v1, s[68:69] nt
	v_add_u32_e32 v1, 0x2c000, v1
	global_load_dwordx4 v[76:79], v1, s[68:69] nt
	v_add_u32_e32 v1, 0x2c000, v1
	global_load_dwordx4 v[80:83], v1, s[68:69] nt
	v_add_u32_e32 v1, 0x2c000, v1
	global_load_dwordx4 v[84:87], v1, s[68:69] nt
	v_add_u32_e32 v1, 0x2c000, v1
	global_load_dwordx4 v[88:91], v1, s[68:69] nt
	v_add_u32_e32 v1, 0x2c000, v1
	global_load_dwordx4 v[92:95], v1, s[68:69] nt
	s_lshl_b32 s70, s55, 8
	s_add_u32 s70, s60, s70
	s_addc_u32 s71, s61, 0
	global_load_dwordx4 v[104:107], v5, s[70:71]
	global_load_dwordx4 v[108:111], v5, s[70:71] offset:16
	s_waitcnt vmcnt(20)
	s_waitcnt lgkmcnt(0)
	ds_write_b32 v2, v112 offset:0
	ds_write_b32 v2, v113 offset:264
	ds_write_b32 v2, v114 offset:528
	ds_write_b32 v2, v115 offset:792
	ds_write_b32 v2, v116 offset:32
	ds_write_b32 v2, v117 offset:296
	ds_write_b32 v2, v118 offset:560
	ds_write_b32 v2, v119 offset:824
	ds_write_b32 v2, v120 offset:64
	ds_write_b32 v2, v121 offset:328
	ds_write_b32 v2, v122 offset:592
	ds_write_b32 v2, v123 offset:856
	ds_write_b32 v2, v124 offset:96
	ds_write_b32 v2, v125 offset:360
	ds_write_b32 v2, v126 offset:624
	ds_write_b32 v2, v127 offset:888
	ds_write_b32 v2, v128 offset:128
	ds_write_b32 v2, v129 offset:392
	ds_write_b32 v2, v130 offset:656
	ds_write_b32 v2, v131 offset:920
	ds_write_b32 v2, v132 offset:160
	ds_write_b32 v2, v133 offset:424
	ds_write_b32 v2, v134 offset:688
	ds_write_b32 v2, v135 offset:952
	ds_write_b32 v2, v136 offset:192
	ds_write_b32 v2, v137 offset:456
	ds_write_b32 v2, v138 offset:720
	ds_write_b32 v2, v139 offset:984
	ds_write_b32 v2, v140 offset:224
	ds_write_b32 v2, v141 offset:488
	ds_write_b32 v2, v142 offset:752
	ds_write_b32 v2, v143 offset:1016
	s_cmp_lt_u32 vcc_lo, 16
	s_cbranch_scc0 .Lmy_cv0_ns
	v_mul_f32_e32 v144, 0x3f4ccccd, v144
	v_mul_f32_e32 v145, 0x3f4ccccd, v145
	v_mul_f32_e32 v146, 0x3f4ccccd, v146
	v_mul_f32_e32 v147, 0x3f4ccccd, v147
	v_mul_f32_e32 v148, 0x3f4ccccd, v148
	v_mul_f32_e32 v149, 0x3f4ccccd, v149
	v_mul_f32_e32 v150, 0x3f4ccccd, v150
	v_mul_f32_e32 v151, 0x3f4ccccd, v151
	s_branch .Lmy_cv0_sd

.LBB0_340:
	s_cmp_gt_u32 s29, 2
	s_cselect_b64 s[0:1], -1, 0
	s_and_b64 s[0:1], s[20:21], s[0:1]
	s_andn2_b64 vcc, exec, s[0:1]
	s_cbranch_vccnz .LBB0_392
	s_waitcnt vmcnt(0)
	v_cmp_eq_u32_e32 vcc, 0, v208
	s_waitcnt vmcnt(0) lgkmcnt(0)
	s_barrier
	v_readfirstlane_b32 s3, v208
	s_nop 3
	s_lshr_b32 s3, s3, 6
	s_cmp_eq_u32 s3, 0
	s_cbranch_scc1 .Lmy_cv1_end
	v_readlane_b32 s36, v238, 0
	v_readlane_b32 s37, v238, 1
	s_mul_i32 s4, s2, 7
	s_add_i32 s4, s4, s3
	s_add_i32 s4, s4, -1
	s_lshl_b32 s72, s3, 14
	s_mov_b32 s3, s4
	s_nop 4
	s_load_dwordx4 s[60:63], s[36:37], 0x60
	s_load_dwordx2 s[64:65], s[36:37], 0x70
	s_load_dwordx2 s[98:99], s[36:37], 0x58
	s_load_dwordx2 s[100:101], s[36:37], 0x48
	v_and_b32_e32 v8, 7, v209
	v_lshrrev_b32_e32 v9, 3, v209
	v_mul_u32_u24_e32 v0, 0x5800, v9
	v_lshl_add_u32 v0, v8, 4, v0
	v_lshlrev_b32_e32 v152, 13, v9
	v_lshl_add_u32 v152, v8, 4, v152
	v_mul_u32_u24_e32 v2, 0x420, v8
	v_lshl_add_u32 v2, v9, 2, v2
	v_add_u32_e32 v2, s72, v2
	v_mul_u32_u24_e32 v3, 0x108, v9
	v_lshl_add_u32 v3, v8, 5, v3
	v_add_u32_e32 v3, s72, v3
	v_lshlrev_b32_e32 v4, 12, v9
	v_lshl_add_u32 v4, v8, 4, v4
	v_lshlrev_b32_e32 v5, 5, v8
	s_waitcnt lgkmcnt(0)
	s_cmpk_lt_u32 s3, 0x200
	s_cbranch_scc0 .Lmy_cv1_no3a
	s_mov_b32 s66, s3
	s_cmpk_ge_u32 s66, 0x1600
	s_cselect_b32 s68, s64, s62
	s_cselect_b32 s69, s65, s63
	s_cselect_b32 s41, 0x1600, 0
	s_sub_u32 s41, s66, s41
	s_mul_hi_u32 vcc_lo, s41, 0xba2e8ba3
	s_lshr_b32 vcc_lo, vcc_lo, 7
	s_mul_i32 s70, vcc_lo, 0xb0
	s_sub_u32 vcc_hi, s41, s70
	s_mul_i32 s70, vcc_lo, 0x160000
	s_lshl_b32 s71, vcc_hi, 7
	s_add_u32 s68, s68, s70
	s_addc_u32 s69, s69, 0
	s_add_u32 s68, s68, s71
	s_addc_u32 s69, s69, 0
	v_mov_b32_e32 v1, v0
	global_load_dwordx4 v[112:115], v1, s[68:69] nt
	v_add_u32_e32 v1, 0x2c000, v1
	global_load_dwordx4 v[116:119], v1, s[68:69] nt
	v_add_u32_e32 v1, 0x2c000, v1
	global_load_dwordx4 v[120:123], v1, s[68:69] nt
	v_add_u32_e32 v1, 0x2c000, v1
	global_load_dwordx4 v[124:127], v1, s[68:69] nt
	v_add_u32_e32 v1, 0x2c000, v1
	global_load_dwordx4 v[128:131], v1, s[68:69] nt
	v_add_u32_e32 v1, 0x2c000, v1
	global_load_dwordx4 v[132:135], v1, s[68:69] nt
	v_add_u32_e32 v1, 0x2c000, v1
	global_load_dwordx4 v[136:139], v1, s[68:69] nt
	v_add_u32_e32 v1, 0x2c000, v1
	global_load_dwordx4 v[140:143], v1, s[68:69] nt
	s_lshl_b32 s70, vcc_lo, 8
	s_add_u32 s70, s60, s70
	s_addc_u32 s71, s61, 0
	global_load_dwordx4 v[144:147], v5, s[70:71]
	global_load_dwordx4 v[148:151], v5, s[70:71] offset:16
	s_branch .Lmy_cv1_dn3a

.LBB0_418:
	s_ashr_i32 s4, s65, 3
	s_ashr_i32 s5, s4, 31
	s_lshl_b32 s75, s66, 7
	s_lshr_b32 s76, s68, 8
	s_and_b32 s71, s70, 3
	s_lshl_b64 s[40:41], s[4:5], 12
	s_ashr_i32 s38, s75, 31
	s_add_u32 s40, s40, s75
	s_addc_u32 s41, s41, s38
	s_lshl_b32 s38, s71, 5
	s_or_b32 s42, s40, s38
	s_mov_b32 s43, s41
	s_lshl_b32 s38, s65, 7
	s_lshl_b64 s[42:43], s[42:43], 11
	s_and_b32 s38, s38, 0x380
	s_lshl_b32 s50, s76, 6
	s_lshl_b64 s[4:5], s[4:5], 23
	s_add_u32 s44, s3, s4
	s_addc_u32 s45, s58, s5
	s_add_u32 s51, s16, s4
	s_addc_u32 s69, s17, s5
	s_lshl_b32 s74, s70, 10
	s_cmp_lg_u32 0, -1
	s_cselect_b32 s48, 0, 0
	s_add_i32 s72, s74, s48
	s_add_u32 s42, s10, s42
	s_addc_u32 s43, s11, s43
	s_lshl_b32 s38, s38, 1
	s_add_u32 s42, s42, s38
	s_addc_u32 s43, s43, 0
	s_lshl_b32 s48, s76, 7
	s_add_u32 s48, s42, s48
	s_addc_u32 s49, s43, 0
	s_add_u32 s44, s44, s38
	s_addc_u32 s45, s45, 0
	s_add_u32 s42, s51, s38
	s_addc_u32 s43, s69, 0
	s_lshl_b32 s69, s70, 4
	s_lshl_b32 s51, s71, 15
	global_load_dwordx4 v[14:17], v[38:39], off
	s_nop 0
	global_load_dwordx4 v[10:13], v[10:11], off offset:1024
	v_add_u32_e32 v226, s69, v215
	s_add_i32 s51, s51, s50
	s_add_i32 s73, s72, 0x10000
	global_load_dwordx4 v[40:43], v[192:193], off
	global_load_dwordx4 v[44:47], v[192:193], off offset:16
	global_load_dwordx4 v[48:51], v[194:195], off
	global_load_dwordx4 v[52:55], v[194:195], off offset:16
	global_load_dwordx4 v[66:69], v[196:197], off
	global_load_dwordx4 v[70:73], v[196:197], off offset:16
	global_load_dwordx4 v[230:233], v[192:193], off offset:2048
	global_load_dwordx4 v[234:237], v[192:193], off offset:2064
	global_load_dwordx4 v[240:243], v[198:199], off
	global_load_dwordx4 v[244:247], v[198:199], off offset:16
	global_load_dwordx4 v[248:251], v[200:201], off
	global_load_dwordx4 v[252:255], v[200:201], off offset:16
	s_mov_b32 s50, m0
	s_mov_b32 m0, s72
	s_nop 0
	global_load_lds_dwordx4 v226, s[44:45]
	s_mov_b32 m0, s50
	s_add_u32 s50, s44, 0x80
	v_add_u32_e32 v227, s51, v216
	s_addc_u32 s51, s45, 0
	s_add_i32 s77, s72, 0x2000
	s_mov_b32 s78, m0
	s_mov_b32 m0, s77
	s_nop 0
	global_load_lds_dwordx4 v226, s[50:51]
	s_mov_b32 m0, s78
	s_mov_b32 s50, m0
	s_mov_b32 m0, s73
	s_nop 0
	global_load_lds_dwordx4 v227, s[42:43]
	s_mov_b32 m0, s50
	s_add_u32 s50, s42, 0x80
	s_addc_u32 s51, s43, 0
	s_add_i32 s77, s72, 0x12000
	s_mov_b32 s78, m0
	s_mov_b32 m0, s77
	s_nop 0
	global_load_lds_dwordx4 v227, s[50:51]
	s_mov_b32 m0, s78
	s_add_u32 s50, s44, 0x20000
	s_addc_u32 s51, s45, 0
	s_add_i32 s77, s72, 0x4000
	s_mov_b32 s78, m0
	s_mov_b32 m0, s77
	s_nop 0
	global_load_lds_dwordx4 v226, s[50:51]
	s_mov_b32 m0, s78
	s_add_u32 s50, s44, 0x20080
	s_addc_u32 s51, s45, 0
	s_add_i32 s77, s72, 0x6000
	s_mov_b32 s78, m0
	s_mov_b32 m0, s77
	s_nop 0
	global_load_lds_dwordx4 v226, s[50:51]
	s_mov_b32 m0, s78
	v_lshlrev_b32_e32 v0, 1, v219
	global_load_dwordx4 v[120:123], v0, s[48:49]
	global_load_dwordx4 v[116:119], v0, s[48:49] offset:32
	global_load_dwordx4 v[112:115], v0, s[48:49] offset:64
	global_load_dwordx4 v[108:111], v0, s[48:49] offset:96
	s_add_u32 s48, s44, 0x40000
	s_addc_u32 s49, s45, 0
	s_add_i32 s50, s72, 0x8000
	s_mov_b32 s51, m0
	s_mov_b32 m0, s50
	s_nop 0
	global_load_lds_dwordx4 v226, s[48:49]
	s_mov_b32 m0, s51
	s_add_u32 s48, s44, 0x40080
	s_addc_u32 s49, s45, 0
	s_add_i32 s50, s72, 0xa000
	s_mov_b32 s51, m0
	s_mov_b32 m0, s50
	s_nop 0
	global_load_lds_dwordx4 v226, s[48:49]
	s_mov_b32 m0, s51
	s_waitcnt vmcnt(6) lgkmcnt(0)
	s_barrier
	v_lshlrev_b32_e32 v58, 16, v30
	v_and_b32_e32 v59, 0xffff0000, v30
	v_lshlrev_b32_e32 v60, 16, v31
	v_and_b32_e32 v61, 0xffff0000, v31
	v_lshlrev_b32_e32 v30, 16, v18
	v_and_b32_e32 v31, 0xffff0000, v18
	v_lshlrev_b32_e32 v18, 16, v19
	v_and_b32_e32 v19, 0xffff0000, v19
	v_lshlrev_b32_e32 v56, 16, v20
	v_and_b32_e32 v57, 0xffff0000, v20
	v_lshlrev_b32_e32 v62, 16, v32
	v_and_b32_e32 v63, 0xffff0000, v32
	v_lshlrev_b32_e32 v64, 16, v33
	v_and_b32_e32 v65, 0xffff0000, v33
	v_lshlrev_b32_e32 v32, 16, v22
	v_and_b32_e32 v33, 0xffff0000, v22
	v_lshlrev_b32_e32 v22, 16, v23
	v_and_b32_e32 v23, 0xffff0000, v23
	v_lshlrev_b32_e32 v74, 16, v24
	v_and_b32_e32 v75, 0xffff0000, v24
	v_lshlrev_b32_e32 v76, 16, v28
	v_and_b32_e32 v77, 0xffff0000, v28
	v_lshlrev_b32_e32 v24, 16, v25
	v_and_b32_e32 v25, 0xffff0000, v25
	v_lshlrev_b32_e32 v34, 16, v26
	v_and_b32_e32 v35, 0xffff0000, v26
	v_lshlrev_b32_e32 v26, 16, v27
	v_and_b32_e32 v27, 0xffff0000, v27
	s_lshl_b64 s[48:49], s[46:47], 12
	s_or_b32 s46, s46, 1
	s_and_b32 s47, s46, 0xfff
	s_cmp_lg_u32 s47, 1
	v_pk_fma_f32 v[30:31], v[40:41], v[30:31], 0 op_sel_hi:[1,1,0]
	v_pk_fma_f32 v[18:19], v[42:43], v[18:19], 0 op_sel_hi:[1,1,0]
	v_pk_fma_f32 v[40:41], v[44:45], v[56:57], 0 op_sel_hi:[1,1,0]
	v_pk_fma_f32 v[18:19], v[50:51], v[22:23], v[18:19]
	v_pk_fma_f32 v[22:23], v[52:53], v[74:75], v[40:41]
	v_pk_fma_f32 v[30:31], v[48:49], v[32:33], v[30:31]
	v_pk_fma_f32 v[22:23], v[70:71], v[62:63], v[22:23]
	v_pk_fma_f32 v[30:31], v[66:67], v[58:59], v[30:31]
	v_pk_mul_f32 v[22:23], v[22:23], v[76:77]
	v_pk_fma_f32 v[18:19], v[68:69], v[60:61], v[18:19]
	v_cvt_pk_bf16_f32 v20, v22, v23
	v_lshlrev_b32_e32 v22, 16, v21
	v_and_b32_e32 v23, 0xffff0000, v21
	v_pk_fma_f32 v[22:23], v[46:47], v[22:23], 0 op_sel_hi:[1,1,0]
	v_pk_mul_f32 v[30:31], v[30:31], v[34:35]
	v_pk_fma_f32 v[22:23], v[54:55], v[24:25], v[22:23]
	v_lshlrev_b32_e32 v24, 16, v29
	v_pk_fma_f32 v[22:23], v[72:73], v[64:65], v[22:23]
	v_and_b32_e32 v25, 0xffff0000, v29
	v_pk_mul_f32 v[26:27], v[18:19], v[26:27]
	v_pk_mul_f32 v[22:23], v[22:23], v[24:25]
	v_cvt_pk_bf16_f32 v18, v30, v31
	v_cvt_pk_bf16_f32 v19, v26, v27
	v_cvt_pk_bf16_f32 v21, v22, v23
	v_lshl_add_u64 v[44:45], v[204:205], 0, s[48:49]
	global_store_dwordx4 v[44:45], v[18:21], off offset:2048
	v_lshlrev_b32_e32 v54, 16, v2
	v_and_b32_e32 v55, 0xffff0000, v2
	v_lshlrev_b32_e32 v2, 16, v3
	v_and_b32_e32 v3, 0xffff0000, v3
	v_lshlrev_b32_e32 v74, 16, v4
	v_and_b32_e32 v75, 0xffff0000, v4
	v_lshlrev_b32_e32 v4, 16, v5
	v_and_b32_e32 v5, 0xffff0000, v5
	v_lshlrev_b32_e32 v56, 16, v6
	v_and_b32_e32 v57, 0xffff0000, v6
	v_lshlrev_b32_e32 v6, 16, v7
	v_and_b32_e32 v7, 0xffff0000, v7
	v_lshlrev_b32_e32 v76, 16, v8
	v_and_b32_e32 v77, 0xffff0000, v8
	v_lshlrev_b32_e32 v8, 16, v9
	v_and_b32_e32 v9, 0xffff0000, v9
	v_lshlrev_b32_e32 v66, 16, v14
	v_and_b32_e32 v67, 0xffff0000, v14
	v_lshlrev_b32_e32 v68, 16, v15
	v_and_b32_e32 v69, 0xffff0000, v15
	v_lshlrev_b32_e32 v70, 16, v16
	v_and_b32_e32 v71, 0xffff0000, v16
	v_lshlrev_b32_e32 v72, 16, v17
	v_and_b32_e32 v73, 0xffff0000, v17
	v_lshlrev_b32_e32 v14, 16, v10
	v_and_b32_e32 v15, 0xffff0000, v10
	v_lshlrev_b32_e32 v10, 16, v11
	v_and_b32_e32 v11, 0xffff0000, v11
	v_lshlrev_b32_e32 v16, 16, v12
	v_and_b32_e32 v17, 0xffff0000, v12
	v_lshlrev_b32_e32 v12, 16, v13
	v_and_b32_e32 v13, 0xffff0000, v13
	v_mov_b32_e32 v34, 0
	v_mov_b32_e32 v46, 0
	v_mov_b32_e32 v47, 0
	v_mov_b32_e32 v48, 0
	s_cselect_b64 s[48:49], -1, 0
	s_cmp_eq_u32 s47, 1
	v_mov_b32_e32 v49, 0
	v_pk_fma_f32 v[18:19], v[230:231], v[54:55], 0 op_sel_hi:[1, 1, 0]
	v_pk_fma_f32 v[2:3], v[232:233], v[2:3], 0 op_sel_hi:[1, 1, 0]
	v_pk_fma_f32 v[20:21], v[234:235], v[74:75], 0 op_sel_hi:[1, 1, 0]
	v_pk_fma_f32 v[4:5], v[236:237], v[4:5], 0 op_sel_hi:[1, 1, 0]
	v_pk_fma_f32 v[18:19], v[240:241], v[56:57], v[18:19]
	v_pk_fma_f32 v[2:3], v[242:243], v[6:7], v[2:3]
	v_pk_fma_f32 v[6:7], v[244:245], v[76:77], v[20:21]
	v_pk_fma_f32 v[4:5], v[246:247], v[8:9], v[4:5]
	v_pk_fma_f32 v[8:9], v[248:249], v[66:67], v[18:19]
	v_pk_fma_f32 v[2:3], v[250:251], v[68:69], v[2:3]
	v_pk_fma_f32 v[6:7], v[252:253], v[70:71], v[6:7]
	v_pk_fma_f32 v[4:5], v[254:255], v[72:73], v[4:5]
	v_pk_mul_f32 v[8:9], v[8:9], v[14:15]
	v_pk_mul_f32 v[10:11], v[2:3], v[10:11]
	v_pk_mul_f32 v[6:7], v[6:7], v[16:17]
	v_pk_mul_f32 v[12:13], v[4:5], v[12:13]
	v_cvt_pk_bf16_f32 v2, v8, v9
	v_cvt_pk_bf16_f32 v3, v10, v11
	v_cvt_pk_bf16_f32 v4, v6, v7
	v_cvt_pk_bf16_f32 v5, v12, v13
	global_store_dwordx4 v[44:45], v[2:5], off offset:3072
	s_cbranch_scc1 .LBB0_420
	global_load_dwordx4 v[46:49], v[36:37], off offset:-2048

.LBB0_422:
	v_lshl_add_u32 v228, s76, 13, v220
	ds_read_b128 v[4:7], v228
	v_lshl_add_u64 v[8:9], v[202:203], 0, s[50:51]
	global_load_dwordx4 v[38:41], v[2:3], off offset:1024
	global_load_dwordx4 v[42:45], v[8:9], off
	ds_read_b128 v[18:21], v228 offset:512
	ds_read_b128 v[74:77], v228 offset:2048
	s_addk_i32 s75, 0x80
	s_ashr_i32 s50, s75, 6
	s_cmp_gt_i32 s50, 2
	s_waitcnt lgkmcnt(2)
	s_waitcnt vmcnt(8)
	v_mfma_f32_32x32x16_bf16 v[2:17], v[4:7], v[120:123], 0
	s_waitcnt lgkmcnt(0)
	v_mfma_f32_32x32x16_bf16 v[2:17], v[74:77], v[116:119], v[2:17]
	ds_read_b128 v[74:77], v228 offset:2560
	v_mfma_f32_32x32x16_bf16 v[18:33], v[18:21], v[120:123], 0
	s_waitcnt lgkmcnt(0)
	v_mfma_f32_32x32x16_bf16 v[18:33], v[74:77], v[116:119], v[18:33]
	ds_read_b128 v[74:77], v228 offset:4096
	s_waitcnt lgkmcnt(0)
	v_mfma_f32_32x32x16_bf16 v[2:17], v[74:77], v[112:115], v[2:17]
	ds_read_b128 v[74:77], v228 offset:4608
	s_waitcnt lgkmcnt(0)
	v_mfma_f32_32x32x16_bf16 v[18:33], v[74:77], v[112:115], v[18:33]
	ds_read_b128 v[74:77], v228 offset:6144
	s_waitcnt lgkmcnt(0)
	v_mfma_f32_32x32x16_bf16 v[2:17], v[74:77], v[108:111], v[2:17]
	ds_read_b128 v[74:77], v228 offset:6656
	s_waitcnt lgkmcnt(0)
	v_mfma_f32_32x32x16_bf16 v[18:33], v[74:77], v[108:111], v[18:33]
	s_nop 15
	s_nop 7
	s_cbranch_scc1 .LBB0_424
	s_sub_i32 s48, 2, s50
	s_lshr_b32 s49, s71, 1
	s_cmp_gt_u32 s48, s49
	s_cselect_b64 vcc, -1, 0
	s_nop 3
	v_cndmask_b32_e32 v17, v17, v225, vcc
	v_cndmask_b32_e32 v16, v16, v225, vcc
	v_cndmask_b32_e32 v15, v15, v225, vcc
	v_cndmask_b32_e32 v14, v14, v225, vcc
	v_cndmask_b32_e32 v13, v13, v225, vcc
	v_cndmask_b32_e32 v12, v12, v225, vcc
	v_cndmask_b32_e32 v11, v11, v225, vcc
	v_cndmask_b32_e32 v10, v10, v225, vcc
	v_cndmask_b32_e32 v9, v9, v225, vcc
	v_cndmask_b32_e32 v8, v8, v225, vcc
	v_cndmask_b32_e32 v7, v7, v225, vcc
	v_cndmask_b32_e32 v6, v6, v225, vcc
	v_cndmask_b32_e32 v5, v5, v225, vcc
	v_cndmask_b32_e32 v4, v4, v225, vcc
	v_cndmask_b32_e32 v3, v3, v225, vcc
	v_cndmask_b32_e32 v2, v2, v225, vcc
	v_cndmask_b32_e32 v33, v33, v225, vcc
	v_cndmask_b32_e32 v32, v32, v225, vcc
	v_cndmask_b32_e32 v31, v31, v225, vcc
	v_cndmask_b32_e32 v30, v30, v225, vcc
	v_cndmask_b32_e32 v29, v29, v225, vcc
	v_cndmask_b32_e32 v28, v28, v225, vcc
	v_cndmask_b32_e32 v27, v27, v225, vcc
	v_cndmask_b32_e32 v26, v26, v225, vcc
	v_cndmask_b32_e32 v25, v25, v225, vcc
	v_cndmask_b32_e32 v24, v24, v225, vcc
	v_cndmask_b32_e32 v23, v23, v225, vcc
	v_cndmask_b32_e32 v22, v22, v225, vcc
	v_cndmask_b32_e32 v21, v21, v225, vcc
	v_cndmask_b32_e32 v20, v20, v225, vcc
	v_cndmask_b32_e32 v19, v19, v225, vcc
	v_cndmask_b32_e32 v18, v18, v225, vcc
.LBB0_424:
	global_load_dwordx4 v[74:77], v[192:193], off
	global_load_dwordx4 v[78:81], v[192:193], off offset:16
	global_load_dwordx4 v[82:85], v[194:195], off
	global_load_dwordx4 v[86:89], v[194:195], off offset:16
	global_load_dwordx4 v[90:93], v[196:197], off
	global_load_dwordx4 v[94:97], v[196:197], off offset:16
	s_waitcnt vmcnt(0) lgkmcnt(0)
	s_barrier
	s_waitcnt vmcnt(10)
	v_lshlrev_b32_e32 v98, 16, v46
	v_and_b32_e32 v99, 0xffff0000, v46
	v_lshlrev_b32_e32 v46, 16, v47
	v_and_b32_e32 v47, 0xffff0000, v47
	v_lshlrev_b32_e32 v104, 16, v48
	v_and_b32_e32 v105, 0xffff0000, v48
	v_lshlrev_b32_e32 v48, 16, v49
	v_and_b32_e32 v49, 0xffff0000, v49
	s_waitcnt vmcnt(9)
	v_lshlrev_b32_e32 v100, 16, v54
	v_and_b32_e32 v101, 0xffff0000, v54
	v_lshlrev_b32_e32 v54, 16, v55
	v_and_b32_e32 v55, 0xffff0000, v55
	v_lshlrev_b32_e32 v106, 16, v56
	v_and_b32_e32 v107, 0xffff0000, v56
	v_lshlrev_b32_e32 v56, 16, v57
	v_and_b32_e32 v57, 0xffff0000, v57
	s_waitcnt vmcnt(8)
	v_lshlrev_b32_e32 v102, 16, v50
	v_and_b32_e32 v103, 0xffff0000, v50
	v_lshlrev_b32_e32 v50, 16, v51
	v_and_b32_e32 v51, 0xffff0000, v51
	v_lshlrev_b32_e32 v124, 16, v52
	v_and_b32_e32 v125, 0xffff0000, v52
	v_lshlrev_b32_e32 v52, 16, v53
	v_and_b32_e32 v53, 0xffff0000, v53
	s_lshl_b64 s[46:47], s[46:47], 12
	v_lshl_add_u64 v[126:127], v[204:205], 0, s[46:47]
	s_add_u32 s46, s44, 0x60000
	s_addc_u32 s47, s45, 0
	s_cmp_lg_u32 0, -1
	s_cselect_b32 s48, 0, 0
	s_add_i32 s51, s48, s74
	s_add_i32 s74, s51, 0xc000
	s_add_u32 s44, s44, 0x60080
	s_addc_u32 s45, s45, 0
	s_add_i32 s75, s51, 0xe000
	s_add_u32 s48, s42, 0x20000
	s_addc_u32 s49, s43, 0
	s_add_i32 s76, s51, 0x14000
	s_add_u32 s42, s42, 0x20080
	s_addc_u32 s43, s43, 0
	s_add_i32 s51, s51, 0x16000
	s_cmp_lg_u32 s66, 0
	s_waitcnt vmcnt(5)
	v_pk_fma_f32 v[74:75], v[74:75], v[98:99], 0 op_sel_hi:[1,1,0]
	v_pk_fma_f32 v[46:47], v[76:77], v[46:47], 0 op_sel_hi:[1,1,0]
	s_waitcnt vmcnt(4)
	v_pk_fma_f32 v[76:77], v[78:79], v[104:105], 0 op_sel_hi:[1,1,0]
	v_pk_fma_f32 v[48:49], v[80:81], v[48:49], 0 op_sel_hi:[1,1,0]
	s_waitcnt vmcnt(3)
	v_pk_fma_f32 v[58:59], v[82:83], v[58:59], v[74:75]
	v_pk_fma_f32 v[46:47], v[84:85], v[60:61], v[46:47]
	s_waitcnt vmcnt(2)
	v_pk_fma_f32 v[60:61], v[86:87], v[62:63], v[76:77]
	v_pk_fma_f32 v[48:49], v[88:89], v[64:65], v[48:49]
	s_waitcnt vmcnt(1)
	v_pk_fma_f32 v[58:59], v[90:91], v[100:101], v[58:59]
	v_pk_fma_f32 v[46:47], v[92:93], v[54:55], v[46:47]
	s_waitcnt vmcnt(0)
	v_pk_fma_f32 v[54:55], v[94:95], v[106:107], v[60:61]
	v_pk_fma_f32 v[48:49], v[96:97], v[56:57], v[48:49]
	v_pk_mul_f32 v[56:57], v[58:59], v[102:103]
	v_pk_mul_f32 v[50:51], v[46:47], v[50:51]
	v_pk_mul_f32 v[54:55], v[54:55], v[124:125]
	v_pk_mul_f32 v[52:53], v[48:49], v[52:53]
	v_cvt_pk_bf16_f32 v46, v56, v57
	v_cvt_pk_bf16_f32 v47, v50, v51
	v_cvt_pk_bf16_f32 v48, v54, v55
	v_cvt_pk_bf16_f32 v49, v52, v53
	global_store_dwordx4 v[126:127], v[46:49], off offset:2048
	v_lshlrev_b32_e32 v78, 16, v34
	v_and_b32_e32 v79, 0xffff0000, v34
	v_lshlrev_b32_e32 v34, 16, v35
	v_and_b32_e32 v35, 0xffff0000, v35
	v_lshlrev_b32_e32 v84, 16, v36
	v_and_b32_e32 v85, 0xffff0000, v36
	v_lshlrev_b32_e32 v36, 16, v37
	v_and_b32_e32 v37, 0xffff0000, v37
	v_lshlrev_b32_e32 v80, 16, v42
	v_and_b32_e32 v81, 0xffff0000, v42
	v_lshlrev_b32_e32 v42, 16, v43
	v_and_b32_e32 v43, 0xffff0000, v43
	v_lshlrev_b32_e32 v86, 16, v44
	v_and_b32_e32 v87, 0xffff0000, v44
	v_lshlrev_b32_e32 v44, 16, v45
	v_and_b32_e32 v45, 0xffff0000, v45
	v_lshlrev_b32_e32 v82, 16, v38
	v_and_b32_e32 v83, 0xffff0000, v38
	v_lshlrev_b32_e32 v38, 16, v39
	v_and_b32_e32 v39, 0xffff0000, v39
	v_lshlrev_b32_e32 v88, 16, v40
	v_and_b32_e32 v89, 0xffff0000, v40
	v_lshlrev_b32_e32 v40, 16, v41
	v_and_b32_e32 v41, 0xffff0000, v41
	v_pk_fma_f32 v[46:47], v[230:231], v[78:79], 0 op_sel_hi:[1, 1, 0]
	v_pk_fma_f32 v[34:35], v[232:233], v[34:35], 0 op_sel_hi:[1, 1, 0]
	v_pk_fma_f32 v[48:49], v[234:235], v[84:85], 0 op_sel_hi:[1, 1, 0]
	v_pk_fma_f32 v[36:37], v[236:237], v[36:37], 0 op_sel_hi:[1, 1, 0]
	v_pk_fma_f32 v[46:47], v[240:241], v[66:67], v[46:47]
	v_pk_fma_f32 v[34:35], v[242:243], v[68:69], v[34:35]
	v_pk_fma_f32 v[48:49], v[244:245], v[70:71], v[48:49]
	v_pk_fma_f32 v[36:37], v[246:247], v[72:73], v[36:37]
	v_pk_fma_f32 v[46:47], v[248:249], v[80:81], v[46:47]
	v_pk_fma_f32 v[34:35], v[250:251], v[42:43], v[34:35]
	v_pk_fma_f32 v[42:43], v[252:253], v[86:87], v[48:49]
	v_pk_fma_f32 v[36:37], v[254:255], v[44:45], v[36:37]
	v_pk_mul_f32 v[44:45], v[46:47], v[82:83]
	v_pk_mul_f32 v[38:39], v[34:35], v[38:39]
	v_pk_mul_f32 v[42:43], v[42:43], v[88:89]
	v_pk_mul_f32 v[40:41], v[36:37], v[40:41]
	v_cvt_pk_bf16_f32 v34, v44, v45
	v_cvt_pk_bf16_f32 v35, v38, v39
	v_cvt_pk_bf16_f32 v36, v42, v43
	v_cvt_pk_bf16_f32 v37, v40, v41
	global_store_dwordx4 v[126:127], v[34:37], off offset:3072
	s_mov_b32 s77, m0
	s_mov_b32 m0, s74
	s_nop 0
	global_load_lds_dwordx4 v226, s[46:47]
	s_mov_b32 m0, s77
	s_mov_b32 s46, m0
	s_mov_b32 m0, s75
	s_nop 0
	global_load_lds_dwordx4 v226, s[44:45]
	s_mov_b32 m0, s46
	s_mov_b32 s44, m0
	s_mov_b32 m0, s76
	s_nop 0
	global_load_lds_dwordx4 v227, s[48:49]
	s_mov_b32 m0, s44
	s_nop 0
	s_mov_b32 s44, m0
	s_mov_b32 m0, s51
	s_nop 0
	global_load_lds_dwordx4 v227, s[42:43]
	s_mov_b32 m0, s44
	ds_read_b128 v[156:159], v228 offset:16384
	ds_read_b128 v[160:163], v228 offset:18432
	s_cbranch_scc0 .LBB0_473
	s_waitcnt vmcnt(6) lgkmcnt(0)
	s_barrier
	s_cbranch_execnz .LBB0_427

.LBB0_475:
	s_cmp_gt_u32 s29, 4
	s_cselect_b64 s[0:1], -1, 0
	s_and_b64 s[0:1], s[36:37], s[0:1]
	s_andn2_b64 vcc, exec, s[0:1]
	s_cbranch_vccnz .LBB0_525
	s_waitcnt vmcnt(0)
	v_cmp_eq_u32_e32 vcc, 0, v208
	s_waitcnt vmcnt(0) lgkmcnt(0)
	s_barrier
	v_readfirstlane_b32 s3, v208
	s_nop 3
	s_lshr_b32 s3, s3, 6
	s_cmp_eq_u32 s3, 0
	s_cbranch_scc1 .Lmy_cv2_end
	v_readlane_b32 s36, v238, 0
	v_readlane_b32 s37, v238, 1
	s_mul_i32 s4, s2, 7
	s_add_i32 s4, s4, s3
	s_add_i32 s4, s4, -1
	s_lshl_b32 s72, s3, 14
	s_mov_b32 s3, s4
	s_nop 4
	s_load_dwordx4 s[60:63], s[36:37], 0x60
	s_load_dwordx2 s[64:65], s[36:37], 0x70
	v_and_b32_e32 v8, 7, v209
	v_lshrrev_b32_e32 v9, 3, v209
	v_mul_u32_u24_e32 v0, 0x5800, v9
	v_lshl_add_u32 v0, v8, 4, v0
	v_lshlrev_b32_e32 v152, 13, v9
	v_lshl_add_u32 v152, v8, 4, v152
	v_mul_u32_u24_e32 v2, 0x420, v8
	v_lshl_add_u32 v2, v9, 2, v2
	v_add_u32_e32 v2, s72, v2
	v_mul_u32_u24_e32 v3, 0x108, v9
	v_lshl_add_u32 v3, v8, 5, v3
	v_add_u32_e32 v3, s72, v3
	v_lshlrev_b32_e32 v4, 12, v9
	v_lshl_add_u32 v4, v8, 4, v4
	v_lshlrev_b32_e32 v5, 5, v8
	s_waitcnt lgkmcnt(0)
	s_add_i32 s66, s3, 7680
	s_cmpk_ge_u32 s66, 0x1600
	s_cselect_b32 s68, s64, s62
	s_cselect_b32 s69, s65, s63
	s_cselect_b32 s54, 128, 0
	s_cselect_b32 s41, 0x1600, 0
	s_sub_u32 s41, s66, s41
	s_mul_hi_u32 s4, s41, 0xba2e8ba3
	s_lshr_b32 s4, s4, 7
	s_mul_i32 s70, s4, 0xb0
	s_sub_u32 s5, s41, s70
	s_mul_i32 s70, s4, 0x160000
	s_lshl_b32 s71, s5, 7
	s_add_u32 s68, s68, s70
	s_addc_u32 s69, s69, 0
	s_add_u32 s68, s68, s71
	s_addc_u32 s69, s69, 0
	v_mov_b32_e32 v1, v0
	global_load_dwordx4 v[32:35], v1, s[68:69] nt
	v_add_u32_e32 v1, 0x2c000, v1
	global_load_dwordx4 v[36:39], v1, s[68:69] nt
	v_add_u32_e32 v1, 0x2c000, v1
	global_load_dwordx4 v[40:43], v1, s[68:69] nt
	v_add_u32_e32 v1, 0x2c000, v1
	global_load_dwordx4 v[44:47], v1, s[68:69] nt
	v_add_u32_e32 v1, 0x2c000, v1
	global_load_dwordx4 v[48:51], v1, s[68:69] nt
	v_add_u32_e32 v1, 0x2c000, v1
	global_load_dwordx4 v[52:55], v1, s[68:69] nt
	v_add_u32_e32 v1, 0x2c000, v1
	global_load_dwordx4 v[56:59], v1, s[68:69] nt
	v_add_u32_e32 v1, 0x2c000, v1
	global_load_dwordx4 v[60:63], v1, s[68:69] nt
	s_lshl_b32 s70, s4, 8
	s_add_u32 s70, s60, s70
	s_addc_u32 s71, s61, 0
	global_load_dwordx4 v[96:99], v5, s[70:71]
	global_load_dwordx4 v[100:103], v5, s[70:71] offset:16
	s_addk_i32 s66, 0x700
	s_cmpk_ge_u32 s66, 0x1600
	s_cselect_b32 s68, s64, s62
	s_cselect_b32 s69, s65, s63
	s_cselect_b32 s40, 128, 0
	s_cselect_b32 s41, 0x1600, 0
	s_sub_u32 s41, s66, s41
	s_mul_hi_u32 s55, s41, 0xba2e8ba3
	s_lshr_b32 s55, s55, 7
	s_mul_i32 s70, s55, 0xb0
	s_sub_u32 s67, s41, s70
	s_mul_i32 s70, s55, 0x160000
	s_lshl_b32 s71, s67, 7
	s_add_u32 s68, s68, s70
	s_addc_u32 s69, s69, 0
	s_add_u32 s68, s68, s71
	s_addc_u32 s69, s69, 0
	v_mov_b32_e32 v1, v0
	global_load_dwordx4 v[64:67], v1, s[68:69] nt
	v_add_u32_e32 v1, 0x2c000, v1
	global_load_dwordx4 v[68:71], v1, s[68:69] nt
	v_add_u32_e32 v1, 0x2c000, v1
	global_load_dwordx4 v[72:75], v1, s[68:69] nt
	v_add_u32_e32 v1, 0x2c000, v1
	global_load_dwordx4 v[76:79], v1, s[68:69] nt
	v_add_u32_e32 v1, 0x2c000, v1
	global_load_dwordx4 v[80:83], v1, s[68:69] nt
	v_add_u32_e32 v1, 0x2c000, v1
	global_load_dwordx4 v[84:87], v1, s[68:69] nt
	v_add_u32_e32 v1, 0x2c000, v1
	global_load_dwordx4 v[88:91], v1, s[68:69] nt
	v_add_u32_e32 v1, 0x2c000, v1
	global_load_dwordx4 v[92:95], v1, s[68:69] nt
	s_lshl_b32 s70, s55, 8
	s_add_u32 s70, s60, s70
	s_addc_u32 s71, s61, 0
	global_load_dwordx4 v[104:107], v5, s[70:71]
	global_load_dwordx4 v[108:111], v5, s[70:71] offset:16
	s_waitcnt vmcnt(10)
	s_waitcnt lgkmcnt(0)
	ds_write_b32 v2, v32 offset:0
	ds_write_b32 v2, v33 offset:264
	ds_write_b32 v2, v34 offset:528
	ds_write_b32 v2, v35 offset:792
	ds_write_b32 v2, v36 offset:32
	ds_write_b32 v2, v37 offset:296
	ds_write_b32 v2, v38 offset:560
	ds_write_b32 v2, v39 offset:824
	ds_write_b32 v2, v40 offset:64
	ds_write_b32 v2, v41 offset:328
	ds_write_b32 v2, v42 offset:592
	ds_write_b32 v2, v43 offset:856
	ds_write_b32 v2, v44 offset:96
	ds_write_b32 v2, v45 offset:360
	ds_write_b32 v2, v46 offset:624
	ds_write_b32 v2, v47 offset:888
	ds_write_b32 v2, v48 offset:128
	ds_write_b32 v2, v49 offset:392
	ds_write_b32 v2, v50 offset:656
	ds_write_b32 v2, v51 offset:920
	ds_write_b32 v2, v52 offset:160
	ds_write_b32 v2, v53 offset:424
	ds_write_b32 v2, v54 offset:688
	ds_write_b32 v2, v55 offset:952
	ds_write_b32 v2, v56 offset:192
	ds_write_b32 v2, v57 offset:456
	ds_write_b32 v2, v58 offset:720
	ds_write_b32 v2, v59 offset:984
	ds_write_b32 v2, v60 offset:224
	ds_write_b32 v2, v61 offset:488
	ds_write_b32 v2, v62 offset:752
	ds_write_b32 v2, v63 offset:1016
	s_lshr_b32 s70, s5, 2
	s_lshl_b32 s70, s70, 8
	s_and_b32 s71, s5, 3
	s_lshl_b32 s71, s71, 5
	s_add_i32 s70, s70, s71
	s_add_i32 s70, s70, s54
	s_lshl_b32 s70, s70, 12
	s_lshl_b32 s71, s4, 7
	s_add_i32 s70, s70, s71
	s_add_u32 s70, s70, 0x2200000
	s_add_u32 s70, s26, s70
	s_addc_u32 s71, s27, 0
	s_waitcnt lgkmcnt(0)
	ds_read_b64 v[160:161], v3 offset:0
	ds_read_b64 v[162:163], v3 offset:8
	ds_read_b64 v[164:165], v3 offset:16
	ds_read_b64 v[166:167], v3 offset:24
	ds_read_b64 v[168:169], v3 offset:2112
	ds_read_b64 v[170:171], v3 offset:2120
	ds_read_b64 v[172:173], v3 offset:2128
	ds_read_b64 v[174:175], v3 offset:2136
	ds_read_b64 v[176:177], v3 offset:4224
	ds_read_b64 v[178:179], v3 offset:4232
	ds_read_b64 v[180:181], v3 offset:4240
	ds_read_b64 v[182:183], v3 offset:4248
	ds_read_b64 v[184:185], v3 offset:6336
	ds_read_b64 v[186:187], v3 offset:6344
	ds_read_b64 v[188:189], v3 offset:6352
	ds_read_b64 v[190:191], v3 offset:6360
	s_waitcnt lgkmcnt(12)
	v_mul_f32_e32 v160, v160, v96
	v_mul_f32_e32 v161, v161, v97
	v_mul_f32_e32 v162, v162, v98
	v_mul_f32_e32 v163, v163, v99
	v_mul_f32_e32 v164, v164, v100
	v_mul_f32_e32 v165, v165, v101
	v_mul_f32_e32 v166, v166, v102
	v_mul_f32_e32 v167, v167, v103
	v_cvt_pk_bf16_f32 v192, v160, v161
	v_cvt_pk_bf16_f32 v193, v162, v163
	v_cvt_pk_bf16_f32 v194, v164, v165
	v_cvt_pk_bf16_f32 v195, v166, v167
	v_mov_b32_e32 v9, v4
	global_store_dwordx4 v9, v[192:195], s[70:71]
	s_waitcnt lgkmcnt(8)
	v_mul_f32_e32 v168, v168, v96
	v_mul_f32_e32 v169, v169, v97
	v_mul_f32_e32 v170, v170, v98
	v_mul_f32_e32 v171, v171, v99
	v_mul_f32_e32 v172, v172, v100
	v_mul_f32_e32 v173, v173, v101
	v_mul_f32_e32 v174, v174, v102
	v_mul_f32_e32 v175, v175, v103
	v_cvt_pk_bf16_f32 v196, v168, v169
	v_cvt_pk_bf16_f32 v197, v170, v171
	v_cvt_pk_bf16_f32 v198, v172, v173
	v_cvt_pk_bf16_f32 v199, v174, v175
	v_add_u32_e32 v9, 0x8000, v9
	global_store_dwordx4 v9, v[196:199], s[70:71]
	s_waitcnt lgkmcnt(4)
	v_mul_f32_e32 v176, v176, v96
	v_mul_f32_e32 v177, v177, v97
	v_mul_f32_e32 v178, v178, v98
	v_mul_f32_e32 v179, v179, v99
	v_mul_f32_e32 v180, v180, v100
	v_mul_f32_e32 v181, v181, v101
	v_mul_f32_e32 v182, v182, v102
	v_mul_f32_e32 v183, v183, v103
	v_cvt_pk_bf16_f32 v200, v176, v177
	v_cvt_pk_bf16_f32 v201, v178, v179
	v_cvt_pk_bf16_f32 v202, v180, v181
	v_cvt_pk_bf16_f32 v203, v182, v183
	v_add_u32_e32 v9, 0x8000, v9
	global_store_dwordx4 v9, v[200:203], s[70:71]
	s_waitcnt lgkmcnt(0)
	v_mul_f32_e32 v184, v184, v96
	v_mul_f32_e32 v185, v185, v97
	v_mul_f32_e32 v186, v186, v98
	v_mul_f32_e32 v187, v187, v99
	v_mul_f32_e32 v188, v188, v100
	v_mul_f32_e32 v189, v189, v101
	v_mul_f32_e32 v190, v190, v102
	v_mul_f32_e32 v191, v191, v103
	v_cvt_pk_bf16_f32 v204, v184, v185
	v_cvt_pk_bf16_f32 v205, v186, v187
	v_cvt_pk_bf16_f32 v206, v188, v189
	v_cvt_pk_bf16_f32 v207, v190, v191
	v_add_u32_e32 v9, 0x8000, v9
	global_store_dwordx4 v9, v[204:207], s[70:71]
	s_waitcnt vmcnt(0)
	s_waitcnt lgkmcnt(0)
	ds_write_b32 v2, v64 offset:0
	ds_write_b32 v2, v65 offset:264
	ds_write_b32 v2, v66 offset:528
	ds_write_b32 v2, v67 offset:792
	ds_write_b32 v2, v68 offset:32
	ds_write_b32 v2, v69 offset:296
	ds_write_b32 v2, v70 offset:560
	ds_write_b32 v2, v71 offset:824
	ds_write_b32 v2, v72 offset:64
	ds_write_b32 v2, v73 offset:328
	ds_write_b32 v2, v74 offset:592
	ds_write_b32 v2, v75 offset:856
	ds_write_b32 v2, v76 offset:96
	ds_write_b32 v2, v77 offset:360
	ds_write_b32 v2, v78 offset:624
	ds_write_b32 v2, v79 offset:888
	ds_write_b32 v2, v80 offset:128
	ds_write_b32 v2, v81 offset:392
	ds_write_b32 v2, v82 offset:656
	ds_write_b32 v2, v83 offset:920
	ds_write_b32 v2, v84 offset:160
	ds_write_b32 v2, v85 offset:424
	ds_write_b32 v2, v86 offset:688
	ds_write_b32 v2, v87 offset:952
	ds_write_b32 v2, v88 offset:192
	ds_write_b32 v2, v89 offset:456
	ds_write_b32 v2, v90 offset:720
	ds_write_b32 v2, v91 offset:984
	ds_write_b32 v2, v92 offset:224
	ds_write_b32 v2, v93 offset:488
	ds_write_b32 v2, v94 offset:752
	ds_write_b32 v2, v95 offset:1016
	s_lshr_b32 s70, s67, 2
	s_lshl_b32 s70, s70, 8
	s_and_b32 s71, s67, 3
	s_lshl_b32 s71, s71, 5
	s_add_i32 s70, s70, s71
	s_add_i32 s70, s70, s40
	s_lshl_b32 s70, s70, 12
	s_lshl_b32 s71, s55, 7
	s_add_i32 s70, s70, s71
	s_add_u32 s70, s70, 0x2200000
	s_add_u32 s70, s26, s70
	s_addc_u32 s71, s27, 0
	s_waitcnt lgkmcnt(0)
	ds_read_b64 v[160:161], v3 offset:0
	ds_read_b64 v[162:163], v3 offset:8
	ds_read_b64 v[164:165], v3 offset:16
	ds_read_b64 v[166:167], v3 offset:24
	ds_read_b64 v[168:169], v3 offset:2112
	ds_read_b64 v[170:171], v3 offset:2120
	ds_read_b64 v[172:173], v3 offset:2128
	ds_read_b64 v[174:175], v3 offset:2136
	ds_read_b64 v[176:177], v3 offset:4224
	ds_read_b64 v[178:179], v3 offset:4232
	ds_read_b64 v[180:181], v3 offset:4240
	ds_read_b64 v[182:183], v3 offset:4248
	ds_read_b64 v[184:185], v3 offset:6336
	ds_read_b64 v[186:187], v3 offset:6344
	ds_read_b64 v[188:189], v3 offset:6352
	ds_read_b64 v[190:191], v3 offset:6360
	s_waitcnt lgkmcnt(12)
	v_mul_f32_e32 v160, v160, v104
	v_mul_f32_e32 v161, v161, v105
	v_mul_f32_e32 v162, v162, v106
	v_mul_f32_e32 v163, v163, v107
	v_mul_f32_e32 v164, v164, v108
	v_mul_f32_e32 v165, v165, v109
	v_mul_f32_e32 v166, v166, v110
	v_mul_f32_e32 v167, v167, v111
	v_cvt_pk_bf16_f32 v192, v160, v161
	v_cvt_pk_bf16_f32 v193, v162, v163
	v_cvt_pk_bf16_f32 v194, v164, v165
	v_cvt_pk_bf16_f32 v195, v166, v167
	v_mov_b32_e32 v9, v4
	global_store_dwordx4 v9, v[192:195], s[70:71]
	s_waitcnt lgkmcnt(8)
	v_mul_f32_e32 v168, v168, v104
	v_mul_f32_e32 v169, v169, v105
	v_mul_f32_e32 v170, v170, v106
	v_mul_f32_e32 v171, v171, v107
	v_mul_f32_e32 v172, v172, v108
	v_mul_f32_e32 v173, v173, v109
	v_mul_f32_e32 v174, v174, v110
	v_mul_f32_e32 v175, v175, v111
	v_cvt_pk_bf16_f32 v196, v168, v169
	v_cvt_pk_bf16_f32 v197, v170, v171
	v_cvt_pk_bf16_f32 v198, v172, v173
	v_cvt_pk_bf16_f32 v199, v174, v175
	v_add_u32_e32 v9, 0x8000, v9
	global_store_dwordx4 v9, v[196:199], s[70:71]
	s_waitcnt lgkmcnt(4)
	v_mul_f32_e32 v176, v176, v104
	v_mul_f32_e32 v177, v177, v105
	v_mul_f32_e32 v178, v178, v106
	v_mul_f32_e32 v179, v179, v107
	v_mul_f32_e32 v180, v180, v108
	v_mul_f32_e32 v181, v181, v109
	v_mul_f32_e32 v182, v182, v110
	v_mul_f32_e32 v183, v183, v111
	v_cvt_pk_bf16_f32 v200, v176, v177
	v_cvt_pk_bf16_f32 v201, v178, v179
	v_cvt_pk_bf16_f32 v202, v180, v181
	v_cvt_pk_bf16_f32 v203, v182, v183
	v_add_u32_e32 v9, 0x8000, v9
	global_store_dwordx4 v9, v[200:203], s[70:71]
	s_waitcnt lgkmcnt(0)
	v_mul_f32_e32 v184, v184, v104
	v_mul_f32_e32 v185, v185, v105
	v_mul_f32_e32 v186, v186, v106
	v_mul_f32_e32 v187, v187, v107
	v_mul_f32_e32 v188, v188, v108
	v_mul_f32_e32 v189, v189, v109
	v_mul_f32_e32 v190, v190, v110
	v_mul_f32_e32 v191, v191, v111
	v_cvt_pk_bf16_f32 v204, v184, v185
	v_cvt_pk_bf16_f32 v205, v186, v187
	v_cvt_pk_bf16_f32 v206, v188, v189
	v_cvt_pk_bf16_f32 v207, v190, v191
	v_add_u32_e32 v9, 0x8000, v9
	global_store_dwordx4 v9, v[204:207], s[70:71]
	s_waitcnt vmcnt(0) lgkmcnt(0)
